# FFN-in loop: both next-tile K stages (16 LDS-DMA loads) prefetched before the epilogue stores; first K-iteration load waits counted so stores stay in flight
# baseline (speedup 1.0000x reference)
; #define STAGE(P, BASE, LD, br, kt) do { const bf16* _gb = BASE + ((long)(br) * (LD) + (long)(kt) * BK); \
;     _Pragma("unroll") for (int _i = 0; _i < 2; ++_i) { \
;       __builtin_amdgcn_global_load_lds((const unsigned*)(_gb + ((&LD == &lda) ? offA[_i] : offB[_i])), \
;         (unsigned*)((char*)(P) + tidx_ * 16 + _i * 8192), 16, 0, 0); } } while (0)
; #define WAIT_V(n) asm volatile("s_waitcnt vmcnt(" #n ")" ::: "memory")
; #define BAR __builtin_amdgcn_s_barrier()
; template <class Epi, int NB>
; DEV void gemm_tile_nb(const bf16* __restrict__ A, int lda, long strideA, const bf16* __restrict__ Bt, int ldb, long strideB, int K, int brow, int bcol, Epi& epi) {
;     ...
;   STAGE(SB(0, 0), Bt, ldb, bcol, 0); STAGE(SA(0, 0), A, lda, brow, 0);
;   STAGE(SB(0, 1), Bt, ldb, bcol + HALF, 0); STAGE(SA(0, 1), A, lda, brow + HALF, 0);
;   if (wr == 1) BAR;
;   WAIT_V(4); BAR;
;   STAGE(SB(1, 0), Bt, ldb, bcol, 1); STAGE(SA(1, 0), A, lda, brow, 1); STAGE(SB(1, 1), Bt, ldb, bcol + HALF, 1);
.Lffn_pf_divd:
	v_and_b32_e32 v162, 63, v179
	v_lshrrev_b32_e32 v163, 6, v179
	s_add_i32 s57, s57, s58
	s_lshl_b32 s57, s57, 19
	s_lshl_b32 s60, s60, 19
	v_lshlrev_b32_e32 v164, 4, v162
	v_and_b32_e32 v165, 32, v162
	s_add_u32 s62, s51, s60
	s_addc_u32 s63, s52, 0
	v_xor_b32_e32 v164, v164, v165
	v_lshrrev_b32_e32 v165, 1, v163
	s_add_u32 s64, s50, s57
	s_addc_u32 s65, s49, 0
	v_lshrrev_b32_e32 v166, 6, v164
	v_and_b32_e32 v167, 1, v163
	s_add_u32 s60, s62, 0x40000
	s_addc_u32 s61, s63, 0
	v_lshl_add_u32 v165, v165, 4, v166
	v_and_b32_e32 v166, 62, v164
	s_add_u32 s68, s64, 0x40000
	s_addc_u32 s69, s65, 0
	v_lshl_or_b32 v166, v167, 6, v166
	v_readfirstlane_b32 s42, v179
	v_lshl_add_u32 v162, v165, 11, v166
	s_lshr_b32 s42, s42, 6
	s_lshl_b32 s42, s42, 10
	v_add_u32_e32 v163, 0x20000, v162
	s_add_i32 s43, s42, s74
	s_mov_b32 m0, s43
	s_add_i32 s43, s43, 0x2000
	global_load_lds_dwordx4 v162, s[62:63]
	s_mov_b32 m0, s43
	s_nop 0
	global_load_lds_dwordx4 v163, s[62:63]
	s_mov_b32 m0, s42
	s_add_i32 s43, s42, 0x2000
	global_load_lds_dwordx4 v162, s[64:65]
	s_mov_b32 m0, s43
	s_add_i32 s43, s42, s12
	global_load_lds_dwordx4 v163, s[64:65]
	s_mov_b32 m0, s43
	s_add_i32 s43, s43, 0x2000
	global_load_lds_dwordx4 v162, s[60:61]
	s_mov_b32 m0, s43
	s_add_i32 s43, s42, 0x4000
	global_load_lds_dwordx4 v163, s[60:61]
	s_mov_b32 m0, s43
	s_add_i32 s43, s42, 0x6000
	global_load_lds_dwordx4 v162, s[68:69]
	s_mov_b32 m0, s43
	s_mov_b32 s98, 1
	global_load_lds_dwordx4 v163, s[68:69]
	s_add_u32 s62, s62, 0x80
	s_addc_u32 s63, s63, 0
	s_add_u32 s64, s64, 0x80
	s_addc_u32 s65, s65, 0
	s_add_u32 s60, s60, 0x80
	s_addc_u32 s61, s61, 0
	s_add_u32 s68, s68, 0x80
	s_addc_u32 s69, s69, 0
	s_add_i32 s43, s42, s13
	s_mov_b32 m0, s43
	s_add_i32 s43, s43, 0x2000
	global_load_lds_dwordx4 v162, s[62:63]
	s_mov_b32 m0, s43
	s_add_i32 s43, s42, 0x8000
	global_load_lds_dwordx4 v163, s[62:63]
	s_mov_b32 m0, s43
	s_add_i32 s43, s42, 0xa000
	global_load_lds_dwordx4 v162, s[64:65]
	s_mov_b32 m0, s43
	s_add_i32 s43, s42, s14
	global_load_lds_dwordx4 v163, s[64:65]
	s_mov_b32 m0, s43
	s_add_i32 s43, s43, 0x2000
	global_load_lds_dwordx4 v162, s[60:61]
	s_mov_b32 m0, s43
	s_add_i32 s43, s42, 0xc000
	global_load_lds_dwordx4 v163, s[60:61]
	s_mov_b32 m0, s43
	s_add_i32 s43, s42, 0xe000
	global_load_lds_dwordx4 v162, s[68:69]
	s_mov_b32 m0, s43
	s_nop 0
	global_load_lds_dwordx4 v163, s[68:69]

; #define STAGE(P, BASE, LD, br, kt) do { const bf16* _gb = BASE + ((long)(br) * (LD) + (long)(kt) * BK); \
;     _Pragma("unroll") for (int _i = 0; _i < 2; ++_i) { \
;       __builtin_amdgcn_global_load_lds((const unsigned*)(_gb + ((&LD == &lda) ? offA[_i] : offB[_i])), \
;         (unsigned*)((char*)(P) + tidx_ * 16 + _i * 8192), 16, 0, 0); } } while (0)
; #define WAIT_V(n) asm volatile("s_waitcnt vmcnt(" #n ")" ::: "memory")
; #define BAR __builtin_amdgcn_s_barrier()
; template <class Epi, int NB>
; DEV void gemm_tile_nb(const bf16* __restrict__ A, int lda, long strideA, const bf16* __restrict__ Bt, int ldb, long strideB, int K, int brow, int bcol, Epi& epi) {
;     ...
;   const int wid = __builtin_amdgcn_readfirstlane(tidx_ >> 6), lane = tidx_ & 63, wr = wid >> 2, wc = wid & 3, fr = lane & 15, fq = lane >> 4;
;   f32x4 acc[2][2][4][2] = {};
;   bf16x8 At[4][2], B0[2][2], B1[2][2];
;   const int nt = K / BK;
;   const int lane_off_ = (fr * 64 + fq * 16) ^ ((fr >> 3) << 5);
;   const int aoff = wr * 8192 + lane_off_, boff = 65536 + wc * 4096 + lane_off_;
;   unsigned offA[2], offB[2];
; #pragma unroll
;   for (int _i = 0; _i < 2; ++_i) { int _r, _c; stage_rc(tidx_ * 16 + _i * 8192, _r, _c); offA[_i] = (unsigned)(_r * lda + _c); offB[_i] = (unsigned)(_r * ldb + _c); }
; #pragma unroll 1
;   for (int br = 0; br < NB; ++br) {
;   STAGE(SB(0, 0), Bt, ldb, bcol, 0); STAGE(SA(0, 0), A, lda, brow, 0);
;   STAGE(SB(0, 1), Bt, ldb, bcol + HALF, 0); STAGE(SA(0, 1), A, lda, brow + HALF, 0);
;   if (wr == 1) BAR;
;   WAIT_V(4); BAR;
;   STAGE(SB(1, 0), Bt, ldb, bcol, 1); STAGE(SA(1, 0), A, lda, brow, 1); STAGE(SB(1, 1), Bt, ldb, bcol + HALF, 1);
.LBB0_959:
	v_and_b32_e32 v143, 15, v23
	s_bfe_u32 s1, s57, 0x20006
	v_bfe_u32 v142, v23, 4, 2
	v_lshlrev_b32_e32 v0, 6, v143
	v_lshlrev_b32_e32 v23, 2, v23
	v_lshl_or_b32 v0, v142, 4, v0
	v_and_b32_e32 v23, 32, v23
	s_lshl_b32 s60, s56, 13
	s_lshl_b32 s61, s1, 12
	v_add_u32_e32 v153, s13, v15
	v_bitop3_b32 v24, v0, s61, v23 bitop3:0xde
	v_bitop3_b32 v23, v0, s60, v23 bitop3:0xde
	s_mov_b64 s[62:63], 0x80
	v_readfirstlane_b32 s60, v153
	v_add_u32_e32 v154, 0x2000, v153
	v_lshl_add_u64 v[2:3], v[2:3], 0, s[62:63]
	s_mov_b32 m0, s60
	v_readfirstlane_b32 s60, v154
	v_add_u32_e32 v155, 0x8000, v146
	s_cmp_eq_u32 s98, 0
	s_cbranch_scc1 .Lffn_w4a
	s_waitcnt vmcnt(20)
	s_branch .Lffn_w4b

; #define STAGE(P, BASE, LD, br, kt) do { const bf16* _gb = BASE + ((long)(br) * (LD) + (long)(kt) * BK); \
;     _Pragma("unroll") for (int _i = 0; _i < 2; ++_i) { \
;       __builtin_amdgcn_global_load_lds((const unsigned*)(_gb + ((&LD == &lda) ? offA[_i] : offB[_i])), \
;         (unsigned*)((char*)(P) + tidx_ * 16 + _i * 8192), 16, 0, 0); } } while (0)
; #define WAIT_V(n) asm volatile("s_waitcnt vmcnt(" #n ")" ::: "memory")
; #define BAR __builtin_amdgcn_s_barrier()
; template <class Epi, int NB>
; DEV void gemm_tile_nb(const bf16* __restrict__ A, int lda, long strideA, const bf16* __restrict__ Bt, int ldb, long strideB, int K, int brow, int bcol, Epi& epi) {
;     ...
;   WAIT_V(4); BAR;
;   STAGE(SB(1, 0), Bt, ldb, bcol, 1); STAGE(SA(1, 0), A, lda, brow, 1); STAGE(SB(1, 1), Bt, ldb, bcol + HALF, 1);
;   WAIT_V(6); BAR;
;   for (int t = 0; t < nt - 2; t += 2) {
.Lffn_w4b:
	s_barrier
	s_cmp_eq_u32 s98, 1
	s_cbranch_scc1 .Lffn_s1s0
	global_load_lds_dwordx4 v[2:3], off
.Lffn_s1s0:
	v_lshl_add_u64 v[2:3], v[6:7], 0, s[62:63]
	s_mov_b32 m0, s60
	v_readfirstlane_b32 s60, v155
	v_add_u32_e32 v156, 0xa000, v146
	s_cbranch_scc1 .Lffn_s1s1
	global_load_lds_dwordx4 v[2:3], off
.Lffn_s1s1:
	v_lshl_add_u64 v[2:3], v[12:13], 0, s[62:63]
	s_mov_b32 m0, s60
	v_readfirstlane_b32 s60, v156
	v_add_u32_e32 v157, s14, v15
	s_cbranch_scc1 .Lffn_s1s2
	global_load_lds_dwordx4 v[2:3], off
.Lffn_s1s2:
	v_lshl_add_u64 v[2:3], v[8:9], 0, s[62:63]
	s_mov_b32 m0, s60
	v_readfirstlane_b32 s60, v157
	v_add_u32_e32 v158, 0x2000, v157
	s_cbranch_scc1 .Lffn_s1s3
	global_load_lds_dwordx4 v[2:3], off
.Lffn_s1s3:
	v_lshl_add_u64 v[2:3], v[10:11], 0, s[62:63]
	s_mov_b32 m0, s60
	v_readfirstlane_b32 s60, v158
	s_cbranch_scc1 .Lffn_s1s4
	global_load_lds_dwordx4 v[2:3], off
.Lffn_s1s4:
	v_lshl_add_u64 v[2:3], v[4:5], 0, s[62:63]
	s_mov_b32 m0, s60
	v_lshlrev_b32_e32 v0, 13, v14
	s_cbranch_scc1 .Lffn_s1s5
	global_load_lds_dwordx4 v[2:3], off
.Lffn_s1s5:
	v_and_b32_e32 v0, 0xffffc000, v0
	v_lshl_add_u32 v0, v16, 10, v0
	v_or_b32_e32 v0, v0, v17
	v_add_u32_sdwa v0, v0, sext(v19) dst_sel:DWORD dst_unused:UNUSED_PAD src0_sel:DWORD src1_sel:WORD_0
	v_lshlrev_b64 v[2:3], 1, v[0:1]
	v_lshlrev_b32_e32 v0, 13, v18
	v_and_b32_e32 v0, 0xffffc000, v0
	v_lshl_add_u32 v0, v20, 10, v0
	v_or_b32_e32 v0, v0, v21
	s_add_u32 s42, s53, s42
	v_add_u32_sdwa v0, v0, sext(v22) dst_sel:DWORD dst_unused:UNUSED_PAD src0_sel:DWORD src1_sel:WORD_0
	s_addc_u32 s43, s54, s43
	v_lshlrev_b64 v[4:5], 1, v[0:1]
	v_lshl_add_u64 v[134:135], s[42:43], 0, v[2:3]
	v_lshl_add_u64 v[136:137], s[42:43], 0, v[4:5]
	s_lshl_b32 s42, s58, 11
	s_lshl_b32 s43, s59, 8
	s_add_i32 s42, s42, s43
	s_ashr_i32 s43, s42, 31
	s_lshl_b64 s[42:43], s[42:43], 11
	s_add_u32 s42, s50, s42
	s_addc_u32 s43, s49, s43
	s_cmp_eq_u32 s98, 0
	s_cbranch_scc1 .Lffn_w6a
	s_waitcnt vmcnt(16)
	s_branch .Lffn_w6b

; #define STAGE(P, BASE, LD, br, kt) do { const bf16* _gb = BASE + ((long)(br) * (LD) + (long)(kt) * BK); \
;     _Pragma("unroll") for (int _i = 0; _i < 2; ++_i) { \
;       __builtin_amdgcn_global_load_lds((const unsigned*)(_gb + ((&LD == &lda) ? offA[_i] : offB[_i])), \
;         (unsigned*)((char*)(P) + tidx_ * 16 + _i * 8192), 16, 0, 0); } } while (0)
; #define LDA(dst, b, h) _Pragma("unroll") for (int m = 0; m < 4; ++m) _Pragma("unroll") for (int k = 0; k < 2; ++k) \
;     dst[m][k] = *reinterpret_cast<const bf16x8*>(smem + (((b) * 2 + (h)) * 16384 + m * 2048 + k * 1024) + aoff)
; #define LDB(dst, b, h) _Pragma("unroll") for (int n = 0; n < 2; ++n) _Pragma("unroll") for (int k = 0; k < 2; ++k) \
;     dst[n][k] = *reinterpret_cast<const bf16x8*>(smem + (((b) * 2 + (h)) * 16384 + n * 2048 + k * 1024) + boff)
; #define MMA(ai, bj, At_, Bt_) do { __builtin_amdgcn_s_setprio(1); \
;     _Pragma("unroll") for (int m = 0; m < 4; ++m) _Pragma("unroll") for (int n = 0; n < 2; ++n) _Pragma("unroll") for (int k = 0; k < 2; ++k) \
;       acc[ai][bj][m][n] = __builtin_amdgcn_mfma_f32_16x16x32_bf16(Bt_[n][k], At_[m][k], acc[ai][bj][m][n], 0, 0, 0); \
;     __builtin_amdgcn_s_setprio(0); } while (0)
; #define WAIT_V(n) asm volatile("s_waitcnt vmcnt(" #n ")" ::: "memory")
; #define WAIT_L(n) asm volatile("s_waitcnt lgkmcnt(" #n ")" ::: "memory")
; #define BAR __builtin_amdgcn_s_barrier()
; #define SCHED __builtin_amdgcn_sched_barrier(0)
; template <class Epi, int NB>
; DEV void gemm_tile_nb(const bf16* __restrict__ A, int lda, long strideA, const bf16* __restrict__ Bt, int ldb, long strideB, int K, int brow, int bcol, Epi& epi) {
;     ...
;     LDB(B0, 0, 0); SCHED; LDA(At, 0, 0); STAGE(SA(1, 1), A, lda, brow + HALF, t + 1);
;     WAIT_L(8); BAR; WAIT_L(0); MMA(0, 0, At, B0); BAR; SCHED;
;     LDB(B1, 0, 1); STAGE(SB(0, 0), Bt, ldb, bcol, t + 2);
;     BAR; WAIT_L(0); MMA(0, 1, At, B1); BAR;
;     LDA(At, 0, 1); STAGE(SA(0, 0), A, lda, brow, t + 2);
;     BAR; WAIT_L(0); MMA(1, 0, At, B0); BAR; SCHED;
;     STAGE(SB(0, 1), Bt, ldb, bcol + HALF, t + 2);
;     WAIT_V(6); BAR; MMA(1, 1, At, B1); BAR;
;     LDB(B0, 1, 0); SCHED; LDA(At, 1, 0); STAGE(SA(0, 1), A, lda, brow + HALF, t + 2);
;     WAIT_L(8); BAR; WAIT_L(0); MMA(0, 0, At, B0); BAR; SCHED;
.LBB0_960:
	s_cmp_eq_u32 s58, -2
	s_cselect_b32 s99, s98, 0
	v_add_u32_e32 v159, 0xc000, v146
	v_lshl_add_u64 v[246:247], v[138:139], 0, s[42:43]
	v_readfirstlane_b32 s59, v159
	v_lshl_add_u64 v[160:161], v[246:247], 0, s[80:81]
	s_mov_b32 m0, s59
	ds_read_b128 v[184:187], v0
	ds_read_b128 v[188:191], v0 offset:1024
	ds_read_b128 v[192:195], v0 offset:2048
	ds_read_b128 v[196:199], v0 offset:3072
	ds_read_b128 v[200:203], v0 offset:4096
	ds_read_b128 v[218:221], v0 offset:5120
	ds_read_b128 v[222:225], v0 offset:6144
	ds_read_b128 v[226:229], v0 offset:7168
	s_cmp_eq_u32 s99, 1
	s_cbranch_scc1 .Lffn_p1a
	global_load_lds_dwordx4 v[160:161], off
.Lffn_p1a:
	v_add_u32_e32 v160, 0xe000, v146
	v_lshl_add_u64 v[248:249], v[140:141], 0, s[42:43]
	v_readfirstlane_b32 s59, v160
	v_lshl_add_u64 v[230:231], v[248:249], 0, s[80:81]
	s_mov_b32 m0, s59
	s_nop 0
	s_cbranch_scc1 .Lffn_p1b
	global_load_lds_dwordx4 v[230:231], off
.Lffn_p1b:
	s_waitcnt lgkmcnt(8)
	s_barrier
	s_waitcnt lgkmcnt(0)
	s_setprio 1
	s_waitcnt lgkmcnt(0)
	v_mfma_f32_16x16x32_bf16 v[126:129], v[162:165], v[184:187], v[126:129]
	v_mfma_f32_16x16x32_bf16 v[122:125], v[170:173], v[184:187], v[122:125]
	v_mfma_f32_16x16x32_bf16 v[118:121], v[162:165], v[192:195], v[118:121]
	v_mfma_f32_16x16x32_bf16 v[114:117], v[170:173], v[192:195], v[114:117]
	v_mfma_f32_16x16x32_bf16 v[110:113], v[162:165], v[200:203], v[110:113]
	v_mfma_f32_16x16x32_bf16 v[106:109], v[170:173], v[200:203], v[106:109]
	v_mfma_f32_16x16x32_bf16 v[102:105], v[162:165], v[222:225], v[102:105]
	v_mfma_f32_16x16x32_bf16 v[98:101], v[170:173], v[222:225], v[98:101]
	v_mfma_f32_16x16x32_bf16 v[126:129], v[166:169], v[188:191], v[126:129]
	v_mfma_f32_16x16x32_bf16 v[122:125], v[174:177], v[188:191], v[122:125]
	v_mfma_f32_16x16x32_bf16 v[118:121], v[166:169], v[196:199], v[118:121]
	v_mfma_f32_16x16x32_bf16 v[114:117], v[174:177], v[196:199], v[114:117]
	v_mfma_f32_16x16x32_bf16 v[110:113], v[166:169], v[218:221], v[110:113]
	v_mfma_f32_16x16x32_bf16 v[106:109], v[174:177], v[218:221], v[106:109]
	v_mfma_f32_16x16x32_bf16 v[102:105], v[166:169], v[226:229], v[102:105]
	v_mfma_f32_16x16x32_bf16 v[98:101], v[174:177], v[226:229], v[98:101]
	s_setprio 0
	s_barrier
	v_lshl_add_u64 v[204:205], v[134:135], 0, s[42:43]
	v_readfirstlane_b32 s59, v144
	v_lshl_add_u64 v[214:215], v[204:205], 0, s[72:73]
	s_mov_b32 m0, s59
	ds_read_b128 v[230:233], v145 offset:16384
	ds_read_b128 v[234:237], v145 offset:17408
	ds_read_b128 v[238:241], v145 offset:18432
	ds_read_b128 v[242:245], v145 offset:19456
	global_load_lds_dwordx4 v[214:215], off
	v_lshl_add_u64 v[214:215], v[136:137], 0, s[42:43]
	v_readfirstlane_b32 s59, v148
	v_lshl_add_u64 v[208:209], v[214:215], 0, s[72:73]
	s_mov_b32 m0, s59
	s_nop 0
	global_load_lds_dwordx4 v[208:209], off
	s_barrier
	s_waitcnt lgkmcnt(0)
	s_setprio 1
	s_waitcnt lgkmcnt(0)
	v_mfma_f32_16x16x32_bf16 v[94:97], v[230:233], v[184:187], v[94:97]
	v_mfma_f32_16x16x32_bf16 v[90:93], v[238:241], v[184:187], v[90:93]
	v_mfma_f32_16x16x32_bf16 v[86:89], v[230:233], v[192:195], v[86:89]
	v_mfma_f32_16x16x32_bf16 v[70:73], v[238:241], v[192:195], v[70:73]
	v_mfma_f32_16x16x32_bf16 v[62:65], v[230:233], v[200:203], v[62:65]
	v_mfma_f32_16x16x32_bf16 v[58:61], v[238:241], v[200:203], v[58:61]
	v_mfma_f32_16x16x32_bf16 v[54:57], v[230:233], v[222:225], v[54:57]
	v_mfma_f32_16x16x32_bf16 v[50:53], v[238:241], v[222:225], v[50:53]
	v_mfma_f32_16x16x32_bf16 v[94:97], v[234:237], v[188:191], v[94:97]
	v_mfma_f32_16x16x32_bf16 v[90:93], v[242:245], v[188:191], v[90:93]
	v_mfma_f32_16x16x32_bf16 v[86:89], v[234:237], v[196:199], v[86:89]
	v_mfma_f32_16x16x32_bf16 v[70:73], v[242:245], v[196:199], v[70:73]
	v_mfma_f32_16x16x32_bf16 v[62:65], v[234:237], v[218:221], v[62:65]
	v_mfma_f32_16x16x32_bf16 v[58:61], v[242:245], v[218:221], v[58:61]
	v_mfma_f32_16x16x32_bf16 v[54:57], v[234:237], v[226:229], v[54:57]
	v_mfma_f32_16x16x32_bf16 v[50:53], v[242:245], v[226:229], v[50:53]
	s_setprio 0
	v_readfirstlane_b32 s59, v146
	v_lshl_add_u64 v[208:209], v[246:247], 0, s[72:73]
	s_mov_b32 m0, s59
	v_readfirstlane_b32 s59, v150
	s_barrier
	ds_read_b128 v[184:187], v0 offset:16384
	ds_read_b128 v[188:191], v0 offset:17408
	ds_read_b128 v[192:195], v0 offset:18432
	ds_read_b128 v[196:199], v0 offset:19456
	ds_read_b128 v[200:203], v0 offset:20480
	ds_read_b128 v[218:221], v0 offset:21504
	ds_read_b128 v[222:225], v0 offset:22528
	ds_read_b128 v[226:229], v0 offset:23552
	global_load_lds_dwordx4 v[208:209], off
	v_lshl_add_u64 v[208:209], v[248:249], 0, s[72:73]
	s_mov_b32 m0, s59
	s_nop 0
	global_load_lds_dwordx4 v[208:209], off
	s_cmp_eq_u32 s99, 1
	s_cbranch_scc1 .Lffn_p3a
	s_waitcnt vmcnt(10)
	s_branch .Lffn_p3b
.Lffn_p3a:
	s_waitcnt vmcnt(18)
.Lffn_p3b:
	s_barrier
	s_waitcnt lgkmcnt(0)
	s_setprio 1
	s_waitcnt lgkmcnt(0)
	v_mfma_f32_16x16x32_bf16 v[46:49], v[162:165], v[184:187], v[46:49]
	v_mfma_f32_16x16x32_bf16 v[42:45], v[170:173], v[184:187], v[42:45]
	v_mfma_f32_16x16x32_bf16 v[38:41], v[162:165], v[192:195], v[38:41]
	v_mfma_f32_16x16x32_bf16 v[34:37], v[170:173], v[192:195], v[34:37]
	v_mfma_f32_16x16x32_bf16 v[30:33], v[162:165], v[200:203], v[30:33]
	v_mfma_f32_16x16x32_bf16 v[26:29], v[170:173], v[200:203], v[26:29]
	v_mfma_f32_16x16x32_bf16 v[22:25], v[162:165], v[222:225], v[22:25]
	v_mfma_f32_16x16x32_bf16 v[18:21], v[170:173], v[222:225], v[18:21]
	v_mfma_f32_16x16x32_bf16 v[46:49], v[166:169], v[188:191], v[46:49]
	v_mfma_f32_16x16x32_bf16 v[42:45], v[174:177], v[188:191], v[42:45]
	v_mfma_f32_16x16x32_bf16 v[38:41], v[166:169], v[196:199], v[38:41]
	v_mfma_f32_16x16x32_bf16 v[34:37], v[174:177], v[196:199], v[34:37]
	v_mfma_f32_16x16x32_bf16 v[30:33], v[166:169], v[218:221], v[30:33]
	v_mfma_f32_16x16x32_bf16 v[26:29], v[174:177], v[218:221], v[26:29]
	v_mfma_f32_16x16x32_bf16 v[22:25], v[166:169], v[226:229], v[22:25]
	v_mfma_f32_16x16x32_bf16 v[18:21], v[174:177], v[226:229], v[18:21]
	s_setprio 0
	s_barrier
	v_readfirstlane_b32 s59, v147
	v_lshl_add_u64 v[162:163], v[204:205], 0, s[82:83]
	s_mov_b32 m0, s59
	v_readfirstlane_b32 s59, v151
	global_load_lds_dwordx4 v[162:163], off
	v_lshl_add_u64 v[162:163], v[214:215], 0, s[82:83]
	s_mov_b32 m0, s59
	s_nop 0
	global_load_lds_dwordx4 v[162:163], off
	ds_read_b128 v[162:165], v145 offset:32768
	ds_read_b128 v[166:169], v145 offset:33792
	ds_read_b128 v[170:173], v145 offset:34816
	ds_read_b128 v[174:177], v145 offset:35840
	s_cmp_eq_u32 s99, 1
	s_cbranch_scc1 .Lffn_p4a
	s_waitcnt vmcnt(6)
	s_branch .Lffn_p4b
; #define STAGE(P, BASE, LD, br, kt) do { const bf16* _gb = BASE + ((long)(br) * (LD) + (long)(kt) * BK); \
;     _Pragma("unroll") for (int _i = 0; _i < 2; ++_i) { \
;       __builtin_amdgcn_global_load_lds((const unsigned*)(_gb + ((&LD == &lda) ? offA[_i] : offB[_i])), \
;         (unsigned*)((char*)(P) + tidx_ * 16 + _i * 8192), 16, 0, 0); } } while (0)
; #define LDA(dst, b, h) _Pragma("unroll") for (int m = 0; m < 4; ++m) _Pragma("unroll") for (int k = 0; k < 2; ++k) \
;     dst[m][k] = *reinterpret_cast<const bf16x8*>(smem + (((b) * 2 + (h)) * 16384 + m * 2048 + k * 1024) + aoff)
; #define LDB(dst, b, h) _Pragma("unroll") for (int n = 0; n < 2; ++n) _Pragma("unroll") for (int k = 0; k < 2; ++k) \
;     dst[n][k] = *reinterpret_cast<const bf16x8*>(smem + (((b) * 2 + (h)) * 16384 + n * 2048 + k * 1024) + boff)
; #define MMA(ai, bj, At_, Bt_) do { __builtin_amdgcn_s_setprio(1); \
;     _Pragma("unroll") for (int m = 0; m < 4; ++m) _Pragma("unroll") for (int n = 0; n < 2; ++n) _Pragma("unroll") for (int k = 0; k < 2; ++k) \
;       acc[ai][bj][m][n] = __builtin_amdgcn_mfma_f32_16x16x32_bf16(Bt_[n][k], At_[m][k], acc[ai][bj][m][n], 0, 0, 0); \
;     __builtin_amdgcn_s_setprio(0); } while (0)
; #define WAIT_V(n) asm volatile("s_waitcnt vmcnt(" #n ")" ::: "memory")
; #define WAIT_L(n) asm volatile("s_waitcnt lgkmcnt(" #n ")" ::: "memory")
; #define BAR __builtin_amdgcn_s_barrier()
; #define SCHED __builtin_amdgcn_sched_barrier(0)
; template <class Epi, int NB>
; DEV void gemm_tile_nb(const bf16* __restrict__ A, int lda, long strideA, const bf16* __restrict__ Bt, int ldb, long strideB, int K, int brow, int bcol, Epi& epi) {
;     ...
;     WAIT_L(8); BAR; WAIT_L(0); MMA(0, 0, At, B0); BAR; SCHED;
;     LDB(B1, 1, 1); STAGE(SB(1, 0), Bt, ldb, bcol, t + 3);
;     BAR; WAIT_L(0); MMA(0, 1, At, B1); BAR;
;     LDA(At, 1, 1); STAGE(SA(1, 0), A, lda, brow, t + 3);
;     BAR; WAIT_L(0); MMA(1, 0, At, B0); BAR; SCHED;
;     STAGE(SB(1, 1), Bt, ldb, bcol + HALF, t + 3);
;     WAIT_V(6); BAR; MMA(1, 1, At, B1); BAR;
.Lffn_p4a:
	s_waitcnt vmcnt(14)
.Lffn_p4b:
	s_barrier
	s_setprio 1
	v_mfma_f32_16x16x32_bf16 v[14:17], v[230:233], v[184:187], v[14:17]
	v_mfma_f32_16x16x32_bf16 v[10:13], v[238:241], v[184:187], v[10:13]
	v_mfma_f32_16x16x32_bf16 v[6:9], v[230:233], v[192:195], v[6:9]
	v_mfma_f32_16x16x32_bf16 v[2:5], v[238:241], v[192:195], v[2:5]
	v_mfma_f32_16x16x32_bf16 v[66:69], v[230:233], v[200:203], v[66:69]
	v_mfma_f32_16x16x32_bf16 v[74:77], v[238:241], v[200:203], v[74:77]
	v_mfma_f32_16x16x32_bf16 v[78:81], v[230:233], v[222:225], v[78:81]
	v_mfma_f32_16x16x32_bf16 v[82:85], v[238:241], v[222:225], v[82:85]
	v_mfma_f32_16x16x32_bf16 v[14:17], v[234:237], v[188:191], v[14:17]
	v_mfma_f32_16x16x32_bf16 v[10:13], v[242:245], v[188:191], v[10:13]
	v_mfma_f32_16x16x32_bf16 v[6:9], v[234:237], v[196:199], v[6:9]
	v_mfma_f32_16x16x32_bf16 v[2:5], v[242:245], v[196:199], v[2:5]
	v_mfma_f32_16x16x32_bf16 v[66:69], v[234:237], v[218:221], v[66:69]
	v_mfma_f32_16x16x32_bf16 v[74:77], v[242:245], v[218:221], v[74:77]
	v_mfma_f32_16x16x32_bf16 v[78:81], v[234:237], v[226:229], v[78:81]
	v_mfma_f32_16x16x32_bf16 v[82:85], v[242:245], v[226:229], v[82:85]
	s_setprio 0
	s_barrier
	v_readfirstlane_b32 s59, v149
	v_lshl_add_u64 v[208:209], v[246:247], 0, s[82:83]
	s_mov_b32 m0, s59
	v_readfirstlane_b32 s59, v152
	ds_read_b128 v[184:187], v0 offset:32768
	ds_read_b128 v[188:191], v0 offset:33792
	ds_read_b128 v[192:195], v0 offset:34816
	ds_read_b128 v[196:199], v0 offset:35840
	ds_read_b128 v[200:203], v0 offset:36864
	ds_read_b128 v[218:221], v0 offset:37888
	ds_read_b128 v[222:225], v0 offset:38912
	ds_read_b128 v[226:229], v0 offset:39936
	global_load_lds_dwordx4 v[208:209], off
	v_lshl_add_u64 v[208:209], v[248:249], 0, s[82:83]
	s_mov_b32 m0, s59
	s_nop 0
	global_load_lds_dwordx4 v[208:209], off
	s_waitcnt lgkmcnt(8)
	s_barrier
	s_waitcnt lgkmcnt(0)
	s_setprio 1
	s_waitcnt lgkmcnt(0)
	v_mfma_f32_16x16x32_bf16 v[126:129], v[162:165], v[184:187], v[126:129]
	v_mfma_f32_16x16x32_bf16 v[122:125], v[170:173], v[184:187], v[122:125]
	v_mfma_f32_16x16x32_bf16 v[118:121], v[162:165], v[192:195], v[118:121]
	v_mfma_f32_16x16x32_bf16 v[114:117], v[170:173], v[192:195], v[114:117]
	v_mfma_f32_16x16x32_bf16 v[110:113], v[162:165], v[200:203], v[110:113]
	v_mfma_f32_16x16x32_bf16 v[106:109], v[170:173], v[200:203], v[106:109]
	v_mfma_f32_16x16x32_bf16 v[102:105], v[162:165], v[222:225], v[102:105]
	v_mfma_f32_16x16x32_bf16 v[98:101], v[170:173], v[222:225], v[98:101]
	v_mfma_f32_16x16x32_bf16 v[126:129], v[166:169], v[188:191], v[126:129]
	v_mfma_f32_16x16x32_bf16 v[122:125], v[174:177], v[188:191], v[122:125]
	v_mfma_f32_16x16x32_bf16 v[118:121], v[166:169], v[196:199], v[118:121]
	v_mfma_f32_16x16x32_bf16 v[114:117], v[174:177], v[196:199], v[114:117]
	v_mfma_f32_16x16x32_bf16 v[110:113], v[166:169], v[218:221], v[110:113]
	v_mfma_f32_16x16x32_bf16 v[106:109], v[174:177], v[218:221], v[106:109]
	v_mfma_f32_16x16x32_bf16 v[102:105], v[166:169], v[226:229], v[102:105]
	v_mfma_f32_16x16x32_bf16 v[98:101], v[174:177], v[226:229], v[98:101]
	s_setprio 0
	s_barrier
	v_readfirstlane_b32 s59, v153
	v_lshl_add_u64 v[208:209], v[204:205], 0, s[84:85]
	s_mov_b32 m0, s59
	v_readfirstlane_b32 s59, v154
	ds_read_b128 v[230:233], v145 offset:49152
	ds_read_b128 v[234:237], v145 offset:50176
	ds_read_b128 v[238:241], v145 offset:51200
	ds_read_b128 v[242:245], v145 offset:52224
	global_load_lds_dwordx4 v[208:209], off
	v_lshl_add_u64 v[208:209], v[214:215], 0, s[84:85]
	s_mov_b32 m0, s59
	s_nop 0
	global_load_lds_dwordx4 v[208:209], off
	s_barrier
	s_waitcnt lgkmcnt(0)
	s_setprio 1
	s_waitcnt lgkmcnt(0)
	v_mfma_f32_16x16x32_bf16 v[94:97], v[230:233], v[184:187], v[94:97]
	v_mfma_f32_16x16x32_bf16 v[90:93], v[238:241], v[184:187], v[90:93]
	v_mfma_f32_16x16x32_bf16 v[86:89], v[230:233], v[192:195], v[86:89]
	v_mfma_f32_16x16x32_bf16 v[70:73], v[238:241], v[192:195], v[70:73]
	v_mfma_f32_16x16x32_bf16 v[62:65], v[230:233], v[200:203], v[62:65]
	v_mfma_f32_16x16x32_bf16 v[58:61], v[238:241], v[200:203], v[58:61]
	v_mfma_f32_16x16x32_bf16 v[54:57], v[230:233], v[222:225], v[54:57]
	v_mfma_f32_16x16x32_bf16 v[50:53], v[238:241], v[222:225], v[50:53]
	v_mfma_f32_16x16x32_bf16 v[94:97], v[234:237], v[188:191], v[94:97]
	v_mfma_f32_16x16x32_bf16 v[90:93], v[242:245], v[188:191], v[90:93]
	v_mfma_f32_16x16x32_bf16 v[86:89], v[234:237], v[196:199], v[86:89]
	v_mfma_f32_16x16x32_bf16 v[70:73], v[242:245], v[196:199], v[70:73]
	v_mfma_f32_16x16x32_bf16 v[62:65], v[234:237], v[218:221], v[62:65]
	v_mfma_f32_16x16x32_bf16 v[58:61], v[242:245], v[218:221], v[58:61]
	v_mfma_f32_16x16x32_bf16 v[54:57], v[234:237], v[226:229], v[54:57]
	v_mfma_f32_16x16x32_bf16 v[50:53], v[242:245], v[226:229], v[50:53]
	s_setprio 0
	v_readfirstlane_b32 s59, v155
	v_lshl_add_u64 v[208:209], v[246:247], 0, s[84:85]
	s_mov_b32 m0, s59
	v_readfirstlane_b32 s59, v156
	s_barrier
	ds_read_b128 v[184:187], v0 offset:49152
	ds_read_b128 v[188:191], v0 offset:50176
	ds_read_b128 v[192:195], v0 offset:51200
	ds_read_b128 v[196:199], v0 offset:52224
	ds_read_b128 v[200:203], v0 offset:53248
	ds_read_b128 v[218:221], v0 offset:54272
	ds_read_b128 v[222:225], v0 offset:55296
	ds_read_b128 v[226:229], v0 offset:56320
	global_load_lds_dwordx4 v[208:209], off
	v_lshl_add_u64 v[208:209], v[248:249], 0, s[84:85]
	s_mov_b32 m0, s59
	s_nop 0
	global_load_lds_dwordx4 v[208:209], off
	s_waitcnt vmcnt(10)
	s_barrier
; #define STAGE(P, BASE, LD, br, kt) do { const bf16* _gb = BASE + ((long)(br) * (LD) + (long)(kt) * BK); \
;     _Pragma("unroll") for (int _i = 0; _i < 2; ++_i) { \
;       __builtin_amdgcn_global_load_lds((const unsigned*)(_gb + ((&LD == &lda) ? offA[_i] : offB[_i])), \
;         (unsigned*)((char*)(P) + tidx_ * 16 + _i * 8192), 16, 0, 0); } } while (0)
; #define LDA(dst, b, h) _Pragma("unroll") for (int m = 0; m < 4; ++m) _Pragma("unroll") for (int k = 0; k < 2; ++k) \
;     dst[m][k] = *reinterpret_cast<const bf16x8*>(smem + (((b) * 2 + (h)) * 16384 + m * 2048 + k * 1024) + aoff)
; #define LDB(dst, b, h) _Pragma("unroll") for (int n = 0; n < 2; ++n) _Pragma("unroll") for (int k = 0; k < 2; ++k) \
;     dst[n][k] = *reinterpret_cast<const bf16x8*>(smem + (((b) * 2 + (h)) * 16384 + n * 2048 + k * 1024) + boff)
; #define MMA(ai, bj, At_, Bt_) do { __builtin_amdgcn_s_setprio(1); \
;     _Pragma("unroll") for (int m = 0; m < 4; ++m) _Pragma("unroll") for (int n = 0; n < 2; ++n) _Pragma("unroll") for (int k = 0; k < 2; ++k) \
;       acc[ai][bj][m][n] = __builtin_amdgcn_mfma_f32_16x16x32_bf16(Bt_[n][k], At_[m][k], acc[ai][bj][m][n], 0, 0, 0); \
;     __builtin_amdgcn_s_setprio(0); } while (0)
; #define WAIT_V(n) asm volatile("s_waitcnt vmcnt(" #n ")" ::: "memory")
; #define WAIT_L(n) asm volatile("s_waitcnt lgkmcnt(" #n ")" ::: "memory")
; #define BAR __builtin_amdgcn_s_barrier()
; #define SCHED __builtin_amdgcn_sched_barrier(0)
; template <class Epi, int NB>
; DEV void gemm_tile_nb(const bf16* __restrict__ A, int lda, long strideA, const bf16* __restrict__ Bt, int ldb, long strideB, int K, int brow, int bcol, Epi& epi) {
;     ...
;     BAR; WAIT_L(0); MMA(1, 0, At, B0); BAR; SCHED;
;     STAGE(SB(1, 1), Bt, ldb, bcol + HALF, t + 3);
;     WAIT_V(6); BAR; MMA(1, 1, At, B1); BAR;
;   }
;   { LDB(B0, 0, 0); LDA(At, 0, 0); STAGE(SA(1, 1), A, lda, brow + HALF, nt - 1);
;     BAR; WAIT_L(0); MMA(0, 0, At, B0); BAR;
;     LDB(B1, 0, 1); BAR; WAIT_L(0); MMA(0, 1, At, B1); BAR;
;     LDA(At, 0, 1); WAIT_V(4); BAR; WAIT_L(0); MMA(1, 0, At, B0); MMA(1, 1, At, B1); BAR; }
	s_waitcnt lgkmcnt(0)
	s_setprio 1
	s_waitcnt lgkmcnt(0)
	v_mfma_f32_16x16x32_bf16 v[46:49], v[162:165], v[184:187], v[46:49]
	v_mfma_f32_16x16x32_bf16 v[42:45], v[170:173], v[184:187], v[42:45]
	v_mfma_f32_16x16x32_bf16 v[38:41], v[162:165], v[192:195], v[38:41]
	v_mfma_f32_16x16x32_bf16 v[34:37], v[170:173], v[192:195], v[34:37]
	v_mfma_f32_16x16x32_bf16 v[30:33], v[162:165], v[200:203], v[30:33]
	v_mfma_f32_16x16x32_bf16 v[26:29], v[170:173], v[200:203], v[26:29]
	v_mfma_f32_16x16x32_bf16 v[22:25], v[162:165], v[222:225], v[22:25]
	v_mfma_f32_16x16x32_bf16 v[18:21], v[170:173], v[222:225], v[18:21]
	v_mfma_f32_16x16x32_bf16 v[46:49], v[166:169], v[188:191], v[46:49]
	v_mfma_f32_16x16x32_bf16 v[42:45], v[174:177], v[188:191], v[42:45]
	v_mfma_f32_16x16x32_bf16 v[38:41], v[166:169], v[196:199], v[38:41]
	v_mfma_f32_16x16x32_bf16 v[34:37], v[174:177], v[196:199], v[34:37]
	v_mfma_f32_16x16x32_bf16 v[30:33], v[166:169], v[218:221], v[30:33]
	v_mfma_f32_16x16x32_bf16 v[26:29], v[174:177], v[218:221], v[26:29]
	v_mfma_f32_16x16x32_bf16 v[22:25], v[166:169], v[226:229], v[22:25]
	v_mfma_f32_16x16x32_bf16 v[18:21], v[174:177], v[226:229], v[18:21]
	s_setprio 0
	s_barrier
	v_readfirstlane_b32 s59, v157
	v_lshl_add_u64 v[162:163], v[204:205], 0, s[86:87]
	s_mov_b32 m0, s59
	v_readfirstlane_b32 s59, v158
	global_load_lds_dwordx4 v[162:163], off
	v_lshl_add_u64 v[162:163], v[214:215], 0, s[86:87]
	s_mov_b32 m0, s59
	s_nop 0
	global_load_lds_dwordx4 v[162:163], off
	ds_read_b128 v[162:165], v145
	ds_read_b128 v[166:169], v145 offset:1024
	ds_read_b128 v[170:173], v145 offset:2048
	ds_read_b128 v[174:177], v145 offset:3072
	s_waitcnt vmcnt(6)
	s_barrier
	s_setprio 1
	v_mfma_f32_16x16x32_bf16 v[14:17], v[230:233], v[184:187], v[14:17]
	v_mfma_f32_16x16x32_bf16 v[10:13], v[238:241], v[184:187], v[10:13]
	v_mfma_f32_16x16x32_bf16 v[6:9], v[230:233], v[192:195], v[6:9]
	v_mfma_f32_16x16x32_bf16 v[2:5], v[238:241], v[192:195], v[2:5]
	v_mfma_f32_16x16x32_bf16 v[66:69], v[230:233], v[200:203], v[66:69]
	v_mfma_f32_16x16x32_bf16 v[74:77], v[238:241], v[200:203], v[74:77]
	v_mfma_f32_16x16x32_bf16 v[78:81], v[230:233], v[222:225], v[78:81]
	v_mfma_f32_16x16x32_bf16 v[82:85], v[238:241], v[222:225], v[82:85]
	v_mfma_f32_16x16x32_bf16 v[14:17], v[234:237], v[188:191], v[14:17]
	v_mfma_f32_16x16x32_bf16 v[10:13], v[242:245], v[188:191], v[10:13]
	v_mfma_f32_16x16x32_bf16 v[6:9], v[234:237], v[196:199], v[6:9]
	v_mfma_f32_16x16x32_bf16 v[2:5], v[242:245], v[196:199], v[2:5]
	v_mfma_f32_16x16x32_bf16 v[66:69], v[234:237], v[218:221], v[66:69]
	v_mfma_f32_16x16x32_bf16 v[74:77], v[242:245], v[218:221], v[74:77]
	v_mfma_f32_16x16x32_bf16 v[78:81], v[234:237], v[226:229], v[78:81]
	v_mfma_f32_16x16x32_bf16 v[82:85], v[242:245], v[226:229], v[82:85]
	s_setprio 0
	s_add_i32 s58, s58, 2
	s_add_u32 s42, s42, 0x100
	s_addc_u32 s43, s43, 0
	s_cmp_lt_u32 s58, 12
	s_barrier
	s_cbranch_scc1 .LBB0_960
	s_mov_b64 s[58:59], 0x780
	v_readfirstlane_b32 s42, v159
	v_lshl_add_u64 v[132:133], v[132:133], 0, s[58:59]
	s_mov_b32 m0, s42
	v_readfirstlane_b32 s42, v160
	ds_read_b128 v[134:137], v145
	ds_read_b128 v[138:141], v145 offset:1024
	ds_read_b128 v[146:149], v145 offset:2048
	ds_read_b128 v[150:153], v145 offset:3072
	ds_read_b128 v[154:157], v0
	ds_read_b128 v[162:165], v0 offset:1024
	ds_read_b128 v[166:169], v0 offset:2048
	ds_read_b128 v[170:173], v0 offset:3072
	ds_read_b128 v[174:177], v0 offset:4096
	ds_read_b128 v[184:187], v0 offset:5120
	ds_read_b128 v[188:191], v0 offset:6144
	ds_read_b128 v[192:195], v0 offset:7168
	global_load_lds_dwordx4 v[132:133], off
	v_lshl_add_u64 v[130:131], v[130:131], 0, s[58:59]
	s_mov_b32 m0, s42
	s_cmpk_gt_u32 s57, 0xff
	global_load_lds_dwordx4 v[130:131], off
	s_barrier
	s_waitcnt lgkmcnt(0)
	s_setprio 1
	s_waitcnt lgkmcnt(0)
	v_mfma_f32_16x16x32_bf16 v[126:129], v[134:137], v[154:157], v[126:129]
	v_mfma_f32_16x16x32_bf16 v[118:121], v[134:137], v[166:169], v[118:121]
	v_mfma_f32_16x16x32_bf16 v[110:113], v[134:137], v[174:177], v[110:113]
	v_mfma_f32_16x16x32_bf16 v[102:105], v[134:137], v[188:191], v[102:105]
	v_mfma_f32_16x16x32_bf16 v[126:129], v[138:141], v[162:165], v[126:129]
	v_mfma_f32_16x16x32_bf16 v[122:125], v[146:149], v[154:157], v[122:125]
	v_mfma_f32_16x16x32_bf16 v[118:121], v[138:141], v[170:173], v[118:121]
	v_mfma_f32_16x16x32_bf16 v[114:117], v[146:149], v[166:169], v[114:117]
	v_mfma_f32_16x16x32_bf16 v[110:113], v[138:141], v[184:187], v[110:113]
	v_mfma_f32_16x16x32_bf16 v[106:109], v[146:149], v[174:177], v[106:109]
	v_mfma_f32_16x16x32_bf16 v[102:105], v[138:141], v[192:195], v[102:105]
	v_mfma_f32_16x16x32_bf16 v[98:101], v[146:149], v[188:191], v[98:101]
	v_mfma_f32_16x16x32_bf16 v[130:133], v[150:153], v[162:165], v[122:125]
	v_mfma_f32_16x16x32_bf16 v[158:161], v[150:153], v[170:173], v[114:117]
	v_mfma_f32_16x16x32_bf16 v[196:199], v[150:153], v[184:187], v[106:109]
	v_mfma_f32_16x16x32_bf16 v[200:203], v[150:153], v[192:195], v[98:101]
	s_setprio 0
	s_barrier
	s_nop 1
	ds_read_b128 v[98:101], v145 offset:16384
	ds_read_b128 v[106:109], v145 offset:17408
	ds_read_b128 v[114:117], v145 offset:18432
	ds_read_b128 v[122:125], v145 offset:19456
	s_barrier
; #define LDA(dst, b, h) _Pragma("unroll") for (int m = 0; m < 4; ++m) _Pragma("unroll") for (int k = 0; k < 2; ++k) \
;     dst[m][k] = *reinterpret_cast<const bf16x8*>(smem + (((b) * 2 + (h)) * 16384 + m * 2048 + k * 1024) + aoff)
; #define LDB(dst, b, h) _Pragma("unroll") for (int n = 0; n < 2; ++n) _Pragma("unroll") for (int k = 0; k < 2; ++k) \
;     dst[n][k] = *reinterpret_cast<const bf16x8*>(smem + (((b) * 2 + (h)) * 16384 + n * 2048 + k * 1024) + boff)
; #define MMA(ai, bj, At_, Bt_) do { __builtin_amdgcn_s_setprio(1); \
;     _Pragma("unroll") for (int m = 0; m < 4; ++m) _Pragma("unroll") for (int n = 0; n < 2; ++n) _Pragma("unroll") for (int k = 0; k < 2; ++k) \
;       acc[ai][bj][m][n] = __builtin_amdgcn_mfma_f32_16x16x32_bf16(Bt_[n][k], At_[m][k], acc[ai][bj][m][n], 0, 0, 0); \
;     __builtin_amdgcn_s_setprio(0); } while (0)
; #define WAIT_V(n) asm volatile("s_waitcnt vmcnt(" #n ")" ::: "memory")
; #define WAIT_L(n) asm volatile("s_waitcnt lgkmcnt(" #n ")" ::: "memory")
; #define BAR __builtin_amdgcn_s_barrier()
; template <class Epi, int NB>
; DEV void gemm_tile_nb(const bf16* __restrict__ A, int lda, long strideA, const bf16* __restrict__ Bt, int ldb, long strideB, int K, int brow, int bcol, Epi& epi) {
;     ...
;     LDA(At, 0, 1); WAIT_V(4); BAR; WAIT_L(0); MMA(1, 0, At, B0); MMA(1, 1, At, B1); BAR; }
;   { LDB(B0, 1, 0); LDA(At, 1, 0); WAIT_V(2); BAR; WAIT_L(0); MMA(0, 0, At, B0); BAR;
	s_waitcnt lgkmcnt(0)
	s_setprio 1
	s_waitcnt lgkmcnt(0)
	v_mfma_f32_16x16x32_bf16 v[94:97], v[98:101], v[154:157], v[94:97]
	v_mfma_f32_16x16x32_bf16 v[86:89], v[98:101], v[166:169], v[86:89]
	v_mfma_f32_16x16x32_bf16 v[70:73], v[114:117], v[166:169], v[70:73]
	v_mfma_f32_16x16x32_bf16 v[62:65], v[98:101], v[174:177], v[62:65]
	v_mfma_f32_16x16x32_bf16 v[58:61], v[114:117], v[174:177], v[58:61]
	v_mfma_f32_16x16x32_bf16 v[54:57], v[98:101], v[188:191], v[54:57]
	v_mfma_f32_16x16x32_bf16 v[50:53], v[114:117], v[188:191], v[50:53]
	v_mfma_f32_16x16x32_bf16 v[94:97], v[106:109], v[162:165], v[94:97]
	v_mfma_f32_16x16x32_bf16 v[90:93], v[114:117], v[154:157], v[90:93]
	v_mfma_f32_16x16x32_bf16 v[86:89], v[106:109], v[170:173], v[86:89]
	v_mfma_f32_16x16x32_bf16 v[70:73], v[122:125], v[170:173], v[70:73]
	v_mfma_f32_16x16x32_bf16 v[62:65], v[106:109], v[184:187], v[62:65]
	v_mfma_f32_16x16x32_bf16 v[58:61], v[122:125], v[184:187], v[58:61]
	v_mfma_f32_16x16x32_bf16 v[54:57], v[106:109], v[192:195], v[54:57]
	v_mfma_f32_16x16x32_bf16 v[50:53], v[122:125], v[192:195], v[50:53]
	v_mfma_f32_16x16x32_bf16 v[154:157], v[122:125], v[162:165], v[90:93]
	s_setprio 0
	s_barrier
	s_nop 0
	ds_read_b128 v[90:93], v0 offset:16384
	ds_read_b128 v[162:165], v0 offset:17408
	ds_read_b128 v[166:169], v0 offset:18432
	ds_read_b128 v[170:173], v0 offset:19456
	ds_read_b128 v[174:177], v0 offset:20480
	ds_read_b128 v[184:187], v0 offset:21504
	ds_read_b128 v[188:191], v0 offset:22528
	ds_read_b128 v[192:195], v0 offset:23552
	s_waitcnt vmcnt(4)
	s_barrier
	s_waitcnt lgkmcnt(0)
	s_setprio 1
	s_waitcnt lgkmcnt(0)
	v_mfma_f32_16x16x32_bf16 v[46:49], v[134:137], v[90:93], v[46:49]
	v_mfma_f32_16x16x32_bf16 v[42:45], v[146:149], v[90:93], v[42:45]
	v_mfma_f32_16x16x32_bf16 v[38:41], v[134:137], v[166:169], v[38:41]
	v_mfma_f32_16x16x32_bf16 v[34:37], v[146:149], v[166:169], v[34:37]
	v_mfma_f32_16x16x32_bf16 v[30:33], v[134:137], v[174:177], v[30:33]
	v_mfma_f32_16x16x32_bf16 v[22:25], v[134:137], v[188:191], v[22:25]
	v_mfma_f32_16x16x32_bf16 v[46:49], v[138:141], v[162:165], v[46:49]
	v_mfma_f32_16x16x32_bf16 v[42:45], v[150:153], v[162:165], v[42:45]
	v_mfma_f32_16x16x32_bf16 v[38:41], v[138:141], v[170:173], v[38:41]
	v_mfma_f32_16x16x32_bf16 v[34:37], v[150:153], v[170:173], v[34:37]
	v_mfma_f32_16x16x32_bf16 v[30:33], v[138:141], v[184:187], v[30:33]
	v_mfma_f32_16x16x32_bf16 v[26:29], v[146:149], v[174:177], v[26:29]
	v_mfma_f32_16x16x32_bf16 v[22:25], v[138:141], v[192:195], v[22:25]
	v_mfma_f32_16x16x32_bf16 v[18:21], v[146:149], v[188:191], v[18:21]
	v_mfma_f32_16x16x32_bf16 v[218:221], v[150:153], v[184:187], v[26:29]
	v_mfma_f32_16x16x32_bf16 v[134:137], v[150:153], v[192:195], v[18:21]
	s_setprio 0
	s_setprio 1
	v_mfma_f32_16x16x32_bf16 v[2:5], v[114:117], v[166:169], v[2:5]
	v_mfma_f32_16x16x32_bf16 v[146:149], v[122:125], v[170:173], v[2:5]
	v_mfma_f32_16x16x32_bf16 v[2:5], v[98:101], v[174:177], v[66:69]
	v_mfma_f32_16x16x32_bf16 v[14:17], v[98:101], v[90:93], v[14:17]
	v_mfma_f32_16x16x32_bf16 v[10:13], v[114:117], v[90:93], v[10:13]
	v_mfma_f32_16x16x32_bf16 v[150:153], v[106:109], v[184:187], v[2:5]
	v_mfma_f32_16x16x32_bf16 v[2:5], v[114:117], v[174:177], v[74:77]
	v_mfma_f32_16x16x32_bf16 v[14:17], v[106:109], v[162:165], v[14:17]
	v_mfma_f32_16x16x32_bf16 v[138:141], v[122:125], v[162:165], v[10:13]
	v_mfma_f32_16x16x32_bf16 v[6:9], v[98:101], v[166:169], v[6:9]
	v_mfma_f32_16x16x32_bf16 v[162:165], v[122:125], v[184:187], v[2:5]
	v_mfma_f32_16x16x32_bf16 v[2:5], v[98:101], v[188:191], v[78:81]
	v_mfma_f32_16x16x32_bf16 v[6:9], v[106:109], v[170:173], v[6:9]
	v_mfma_f32_16x16x32_bf16 v[166:169], v[106:109], v[192:195], v[2:5]
	v_mfma_f32_16x16x32_bf16 v[2:5], v[114:117], v[188:191], v[82:85]
	v_mfma_f32_16x16x32_bf16 v[170:173], v[122:125], v[192:195], v[2:5]
	s_setprio 0
	s_barrier
	s_nop 4
	ds_read_b128 v[2:5], v145 offset:32768
	ds_read_b128 v[10:13], v145 offset:33792
	ds_read_b128 v[174:177], v145 offset:34816
	ds_read_b128 v[184:187], v145 offset:35840
	ds_read_b128 v[18:21], v0 offset:32768
	ds_read_b128 v[26:29], v0 offset:33792
	ds_read_b128 v[78:81], v0 offset:34816
	ds_read_b128 v[188:191], v0 offset:35840
	ds_read_b128 v[192:195], v0 offset:36864
	ds_read_b128 v[222:225], v0 offset:37888
	ds_read_b128 v[226:229], v0 offset:38912
	ds_read_b128 v[230:233], v0 offset:39936
	s_waitcnt vmcnt(2)
	s_barrier
; #define LDA(dst, b, h) _Pragma("unroll") for (int m = 0; m < 4; ++m) _Pragma("unroll") for (int k = 0; k < 2; ++k) \
;     dst[m][k] = *reinterpret_cast<const bf16x8*>(smem + (((b) * 2 + (h)) * 16384 + m * 2048 + k * 1024) + aoff)
; #define LDB(dst, b, h) _Pragma("unroll") for (int n = 0; n < 2; ++n) _Pragma("unroll") for (int k = 0; k < 2; ++k) \
;     dst[n][k] = *reinterpret_cast<const bf16x8*>(smem + (((b) * 2 + (h)) * 16384 + n * 2048 + k * 1024) + boff)
; #define MMA(ai, bj, At_, Bt_) do { __builtin_amdgcn_s_setprio(1); \
;     _Pragma("unroll") for (int m = 0; m < 4; ++m) _Pragma("unroll") for (int n = 0; n < 2; ++n) _Pragma("unroll") for (int k = 0; k < 2; ++k) \
;       acc[ai][bj][m][n] = __builtin_amdgcn_mfma_f32_16x16x32_bf16(Bt_[n][k], At_[m][k], acc[ai][bj][m][n], 0, 0, 0); \
;     __builtin_amdgcn_s_setprio(0); } while (0)
; #define WAIT_V(n) asm volatile("s_waitcnt vmcnt(" #n ")" ::: "memory")
; #define WAIT_L(n) asm volatile("s_waitcnt lgkmcnt(" #n ")" ::: "memory")
; #define BAR __builtin_amdgcn_s_barrier()
; template <class Epi, int NB>
; DEV void gemm_tile_nb(const bf16* __restrict__ A, int lda, long strideA, const bf16* __restrict__ Bt, int ldb, long strideB, int K, int brow, int bcol, Epi& epi) {
;     ...
;   { LDB(B0, 1, 0); LDA(At, 1, 0); WAIT_V(2); BAR; WAIT_L(0); MMA(0, 0, At, B0); BAR;
;     LDB(B1, 1, 1); WAIT_V(0); BAR; WAIT_L(0); MMA(0, 1, At, B1); BAR;
;     LDA(At, 1, 1); BAR; WAIT_L(0); MMA(1, 0, At, B0); MMA(1, 1, At, B1); BAR; }
;   if (wr == 0) BAR;
	s_waitcnt lgkmcnt(0)
	s_setprio 1
	s_waitcnt lgkmcnt(0)
	v_mfma_f32_16x16x32_bf16 v[66:69], v[2:5], v[18:21], v[126:129]
	v_mfma_f32_16x16x32_bf16 v[122:125], v[10:13], v[26:29], v[66:69]
	v_mfma_f32_16x16x32_bf16 v[66:69], v[174:177], v[18:21], v[130:133]
	v_mfma_f32_16x16x32_bf16 v[114:117], v[184:187], v[26:29], v[66:69]
	v_mfma_f32_16x16x32_bf16 v[66:69], v[2:5], v[78:81], v[118:121]
	v_mfma_f32_16x16x32_bf16 v[106:109], v[10:13], v[188:191], v[66:69]
	v_mfma_f32_16x16x32_bf16 v[66:69], v[174:177], v[78:81], v[158:161]
	v_mfma_f32_16x16x32_bf16 v[98:101], v[184:187], v[188:191], v[66:69]
	v_mfma_f32_16x16x32_bf16 v[66:69], v[2:5], v[192:195], v[110:113]
	v_mfma_f32_16x16x32_bf16 v[90:93], v[10:13], v[222:225], v[66:69]
	v_mfma_f32_16x16x32_bf16 v[66:69], v[174:177], v[192:195], v[196:199]
	v_mfma_f32_16x16x32_bf16 v[82:85], v[184:187], v[222:225], v[66:69]
	v_mfma_f32_16x16x32_bf16 v[66:69], v[2:5], v[226:229], v[102:105]
	v_mfma_f32_16x16x32_bf16 v[74:77], v[10:13], v[230:233], v[66:69]
	v_mfma_f32_16x16x32_bf16 v[66:69], v[174:177], v[226:229], v[200:203]
	v_mfma_f32_16x16x32_bf16 v[66:69], v[184:187], v[230:233], v[66:69]
	s_setprio 0
	s_barrier
	ds_read_b128 v[130:133], v145 offset:49152
	ds_read_b128 v[158:161], v145 offset:50176
	ds_read_b128 v[196:199], v145 offset:51200
	ds_read_b128 v[200:203], v145 offset:52224
	s_waitcnt vmcnt(0)
	s_barrier
	s_waitcnt lgkmcnt(0)
	s_setprio 1
	s_waitcnt lgkmcnt(0)
	v_mfma_f32_16x16x32_bf16 v[94:97], v[130:133], v[18:21], v[94:97]
	v_mfma_f32_16x16x32_bf16 v[18:21], v[196:199], v[18:21], v[154:157]
	v_mfma_f32_16x16x32_bf16 v[118:121], v[200:203], v[26:29], v[18:21]
	v_mfma_f32_16x16x32_bf16 v[18:21], v[130:133], v[78:81], v[86:89]
	v_mfma_f32_16x16x32_bf16 v[110:113], v[158:161], v[188:191], v[18:21]
	v_mfma_f32_16x16x32_bf16 v[18:21], v[196:199], v[78:81], v[70:73]
	v_mfma_f32_16x16x32_bf16 v[102:105], v[200:203], v[188:191], v[18:21]
	v_mfma_f32_16x16x32_bf16 v[18:21], v[130:133], v[192:195], v[62:65]
	v_mfma_f32_16x16x32_bf16 v[126:129], v[158:161], v[26:29], v[94:97]
	v_mfma_f32_16x16x32_bf16 v[94:97], v[158:161], v[222:225], v[18:21]
	v_mfma_f32_16x16x32_bf16 v[18:21], v[196:199], v[192:195], v[58:61]
	v_mfma_f32_16x16x32_bf16 v[86:89], v[200:203], v[222:225], v[18:21]
	v_mfma_f32_16x16x32_bf16 v[18:21], v[130:133], v[226:229], v[54:57]
	v_mfma_f32_16x16x32_bf16 v[78:81], v[158:161], v[230:233], v[18:21]
	v_mfma_f32_16x16x32_bf16 v[18:21], v[196:199], v[226:229], v[50:53]
	v_mfma_f32_16x16x32_bf16 v[70:73], v[200:203], v[230:233], v[18:21]
	s_setprio 0
	s_barrier
	ds_read_b128 v[54:57], v0 offset:49152
	ds_read_b128 v[154:157], v0 offset:50176
	ds_read_b128 v[188:191], v0 offset:51200
	ds_read_b128 v[192:195], v0 offset:52224
	ds_read_b128 v[222:225], v0 offset:53248
	ds_read_b128 v[226:229], v0 offset:54272
	ds_read_b128 v[230:233], v0 offset:55296
	ds_read_b128 v[234:237], v0 offset:56320
	s_barrier
	s_waitcnt lgkmcnt(0)
	s_setprio 1
	s_waitcnt lgkmcnt(0)
	v_mfma_f32_16x16x32_bf16 v[18:21], v[2:5], v[54:57], v[46:49]
	v_mfma_f32_16x16x32_bf16 v[58:61], v[10:13], v[154:157], v[18:21]
	v_mfma_f32_16x16x32_bf16 v[18:21], v[174:177], v[54:57], v[42:45]
	v_mfma_f32_16x16x32_bf16 v[50:53], v[184:187], v[154:157], v[18:21]
	v_mfma_f32_16x16x32_bf16 v[18:21], v[2:5], v[188:191], v[38:41]
	v_mfma_f32_16x16x32_bf16 v[42:45], v[10:13], v[192:195], v[18:21]
	v_mfma_f32_16x16x32_bf16 v[18:21], v[174:177], v[188:191], v[34:37]
	v_mfma_f32_16x16x32_bf16 v[34:37], v[184:187], v[192:195], v[18:21]
	v_mfma_f32_16x16x32_bf16 v[18:21], v[2:5], v[222:225], v[30:33]
	v_mfma_f32_16x16x32_bf16 v[2:5], v[2:5], v[230:233], v[22:25]
	v_mfma_f32_16x16x32_bf16 v[26:29], v[10:13], v[226:229], v[18:21]
	v_mfma_f32_16x16x32_bf16 v[18:21], v[174:177], v[222:225], v[218:221]
	v_mfma_f32_16x16x32_bf16 v[10:13], v[10:13], v[234:237], v[2:5]
	v_mfma_f32_16x16x32_bf16 v[2:5], v[174:177], v[230:233], v[134:137]
	v_mfma_f32_16x16x32_bf16 v[18:21], v[184:187], v[226:229], v[18:21]
	v_mfma_f32_16x16x32_bf16 v[2:5], v[184:187], v[234:237], v[2:5]
	s_setprio 0
	s_setprio 1
	v_mfma_f32_16x16x32_bf16 v[6:9], v[130:133], v[188:191], v[6:9]
	v_mfma_f32_16x16x32_bf16 v[46:49], v[158:161], v[192:195], v[6:9]
	v_mfma_f32_16x16x32_bf16 v[6:9], v[196:199], v[188:191], v[146:149]
	v_mfma_f32_16x16x32_bf16 v[38:41], v[200:203], v[192:195], v[6:9]
	v_mfma_f32_16x16x32_bf16 v[6:9], v[130:133], v[222:225], v[150:153]
	v_mfma_f32_16x16x32_bf16 v[14:17], v[130:133], v[54:57], v[14:17]
	v_mfma_f32_16x16x32_bf16 v[30:33], v[158:161], v[226:229], v[6:9]
	v_mfma_f32_16x16x32_bf16 v[6:9], v[196:199], v[222:225], v[162:165]
	v_mfma_f32_16x16x32_bf16 v[62:65], v[158:161], v[154:157], v[14:17]
	v_mfma_f32_16x16x32_bf16 v[14:17], v[196:199], v[54:57], v[138:141]
	v_mfma_f32_16x16x32_bf16 v[22:25], v[200:203], v[226:229], v[6:9]
	v_mfma_f32_16x16x32_bf16 v[6:9], v[130:133], v[230:233], v[166:169]
	v_mfma_f32_16x16x32_bf16 v[54:57], v[200:203], v[154:157], v[14:17]
	v_mfma_f32_16x16x32_bf16 v[14:17], v[158:161], v[234:237], v[6:9]
	v_mfma_f32_16x16x32_bf16 v[6:9], v[196:199], v[230:233], v[170:173]
	v_mfma_f32_16x16x32_bf16 v[6:9], v[200:203], v[234:237], v[6:9]
	s_setprio 0
	s_barrier
	s_cbranch_scc1 .LBB0_956
	s_barrier
	s_branch .LBB0_956
